# cross-attention loop: MFMA-to-VALU hazard window after the QK chain filled with the K base advance and the canonical running max (pad shortened)
# speedup vs baseline: 1.0073x; 1.0027x over previous
.Lxa_tile:
	s_waitcnt lgkmcnt(7)
	v_mfma_f32_32x32x16_bf16 v[66:81], v[114:117], v[82:85], 0
	ds_read_b128 v[146:149], v181
	s_waitcnt lgkmcnt(7)
	v_mfma_f32_32x32x16_bf16 v[66:81], v[118:121], v[86:89], v[66:81]
	ds_read_b128 v[162:165], v181 offset:1024
	s_waitcnt lgkmcnt(7)
	v_mfma_f32_32x32x16_bf16 v[66:81], v[122:125], v[90:93], v[66:81]
	ds_read_b128 v[150:153], v181 offset:2048
	s_waitcnt lgkmcnt(7)
	v_mfma_f32_32x32x16_bf16 v[66:81], v[126:129], v[94:97], v[66:81]
	ds_read_b128 v[166:169], v181 offset:3072
	s_waitcnt lgkmcnt(7)
	v_mfma_f32_32x32x16_bf16 v[66:81], v[130:133], v[98:101], v[66:81]
	ds_read_b128 v[154:157], v181 offset:4096
	s_waitcnt lgkmcnt(7)
	v_mfma_f32_32x32x16_bf16 v[66:81], v[134:137], v[102:105], v[66:81]
	ds_read_b128 v[170:173], v181 offset:5120
	s_waitcnt lgkmcnt(7)
	v_mfma_f32_32x32x16_bf16 v[66:81], v[138:141], v[106:109], v[66:81]
	ds_read_b128 v[158:161], v181 offset:6144
	s_waitcnt lgkmcnt(7)
	v_mfma_f32_32x32x16_bf16 v[66:81], v[142:145], v[110:113], v[66:81]
	ds_read_b128 v[174:177], v181 offset:7168
	v_add_u32_e32 v180, 0x2000, v180
	v_max_f32_e32 v237, v248, v248
	s_nop 9
	v_max3_f32 v212, v66, v67, v68
	v_max3_f32 v213, v69, v70, v71
	v_max3_f32 v220, v72, v73, v74
	v_max3_f32 v221, v75, v76, v77
	v_max3_f32 v238, v78, v79, v80
	v_max3_f32 v212, v212, v213, v220
	v_max3_f32 v221, v221, v238, v81
	v_max_f32_e32 v212, v212, v221
	v_mov_b32_e32 v213, v212
	s_nop 1
	v_permlane32_swap_b32_e32 v212, v213
	v_max_f32_e32 v212, v212, v213
	v_mul_f32_e32 v212, 0x3e0293ee, v212
	v_max_f32_e32 v220, v237, v212
	v_fma_f32 v66, v66, s67, -v220
	v_fma_f32 v67, v67, s67, -v220
	v_fma_f32 v68, v68, s67, -v220
	v_fma_f32 v69, v69, s67, -v220
	v_fma_f32 v70, v70, s67, -v220
	v_fma_f32 v71, v71, s67, -v220
	v_fma_f32 v72, v72, s67, -v220
	v_fma_f32 v73, v73, s67, -v220
	v_fma_f32 v74, v74, s67, -v220
	v_fma_f32 v75, v75, s67, -v220
	v_fma_f32 v76, v76, s67, -v220
	v_fma_f32 v77, v77, s67, -v220
	v_fma_f32 v78, v78, s67, -v220
	v_fma_f32 v79, v79, s67, -v220
	v_fma_f32 v80, v80, s67, -v220
	v_fma_f32 v81, v81, s67, -v220
	s_waitcnt lgkmcnt(0)
	ds_read_b128 v[114:117], v180
	ds_read_b128 v[118:121], v180 offset:1024
	ds_read_b128 v[122:125], v180 offset:2048
	ds_read_b128 v[126:129], v180 offset:3072
	ds_read_b128 v[130:133], v180 offset:4096
	ds_read_b128 v[134:137], v180 offset:5120
	ds_read_b128 v[138:141], v180 offset:6144
	ds_read_b128 v[142:145], v180 offset:7168
	v_exp_f32_e32 v66, v66
	v_exp_f32_e32 v67, v67
	v_add_f32_e32 v221, 0, v66
	v_exp_f32_e32 v68, v68
	v_add_f32_e32 v221, v67, v221
	v_exp_f32_e32 v69, v69
	v_add_f32_e32 v221, v68, v221
	v_exp_f32_e32 v70, v70
	v_add_f32_e32 v221, v69, v221
	v_exp_f32_e32 v71, v71
	v_add_f32_e32 v221, v70, v221
	v_exp_f32_e32 v72, v72
	v_add_f32_e32 v221, v71, v221
	v_exp_f32_e32 v73, v73
	v_add_f32_e32 v221, v72, v221
	v_exp_f32_e32 v74, v74
	v_add_f32_e32 v221, v73, v221
	v_exp_f32_e32 v75, v75
	v_add_f32_e32 v221, v74, v221
	v_exp_f32_e32 v76, v76
	v_add_f32_e32 v221, v75, v221
	v_exp_f32_e32 v77, v77
	v_add_f32_e32 v221, v76, v221
	v_exp_f32_e32 v78, v78
	v_add_f32_e32 v221, v77, v221
	v_exp_f32_e32 v79, v79
	v_add_f32_e32 v221, v78, v221
	v_exp_f32_e32 v80, v80
	v_add_f32_e32 v221, v79, v221
	v_exp_f32_e32 v81, v81
	v_add_f32_e32 v221, v80, v221
	v_sub_f32_e32 v213, v248, v220
	v_add_f32_e32 v221, v81, v221
	v_exp_f32_e32 v236, v213
	v_mov_b32_e32 v238, v221
	v_mov_b32_e32 v248, v220
	v_cmp_neq_f32_e32 vcc, 1.0, v236
	v_permlane32_swap_b32_e32 v221, v238
	s_cbranch_vccz .Lxa_noresc
	v_pk_mul_f32 v[64:65], v[64:65], v[236:237] op_sel_hi:[1,0]
	v_pk_mul_f32 v[62:63], v[62:63], v[236:237] op_sel_hi:[1,0]
	v_pk_mul_f32 v[60:61], v[60:61], v[236:237] op_sel_hi:[1,0]
	v_pk_mul_f32 v[58:59], v[58:59], v[236:237] op_sel_hi:[1,0]
	v_pk_mul_f32 v[56:57], v[56:57], v[236:237] op_sel_hi:[1,0]
	v_pk_mul_f32 v[54:55], v[54:55], v[236:237] op_sel_hi:[1,0]
	v_pk_mul_f32 v[52:53], v[52:53], v[236:237] op_sel_hi:[1,0]
	v_pk_mul_f32 v[50:51], v[50:51], v[236:237] op_sel_hi:[1,0]
	v_pk_mul_f32 v[48:49], v[48:49], v[236:237] op_sel_hi:[1,0]
	v_pk_mul_f32 v[46:47], v[46:47], v[236:237] op_sel_hi:[1,0]
	v_pk_mul_f32 v[44:45], v[44:45], v[236:237] op_sel_hi:[1,0]
	v_pk_mul_f32 v[42:43], v[42:43], v[236:237] op_sel_hi:[1,0]
	v_pk_mul_f32 v[40:41], v[40:41], v[236:237] op_sel_hi:[1,0]
	v_pk_mul_f32 v[38:39], v[38:39], v[236:237] op_sel_hi:[1,0]
	v_pk_mul_f32 v[36:37], v[36:37], v[236:237] op_sel_hi:[1,0]
	v_pk_mul_f32 v[34:35], v[34:35], v[236:237] op_sel_hi:[1,0]
	v_pk_mul_f32 v[32:33], v[32:33], v[236:237] op_sel_hi:[1,0]
	v_pk_mul_f32 v[30:31], v[30:31], v[236:237] op_sel_hi:[1,0]
	v_pk_mul_f32 v[28:29], v[28:29], v[236:237] op_sel_hi:[1,0]
	v_pk_mul_f32 v[26:27], v[26:27], v[236:237] op_sel_hi:[1,0]
	v_pk_mul_f32 v[24:25], v[24:25], v[236:237] op_sel_hi:[1,0]
	v_pk_mul_f32 v[22:23], v[22:23], v[236:237] op_sel_hi:[1,0]
	v_pk_mul_f32 v[20:21], v[20:21], v[236:237] op_sel_hi:[1,0]
	v_pk_mul_f32 v[18:19], v[18:19], v[236:237] op_sel_hi:[1,0]
	v_pk_mul_f32 v[16:17], v[16:17], v[236:237] op_sel_hi:[1,0]
	v_pk_mul_f32 v[14:15], v[14:15], v[236:237] op_sel_hi:[1,0]
	v_pk_mul_f32 v[12:13], v[12:13], v[236:237] op_sel_hi:[1,0]
	v_pk_mul_f32 v[10:11], v[10:11], v[236:237] op_sel_hi:[1,0]
	v_pk_mul_f32 v[8:9], v[8:9], v[236:237] op_sel_hi:[1,0]
	v_pk_mul_f32 v[6:7], v[6:7], v[236:237] op_sel_hi:[1,0]
	v_pk_mul_f32 v[4:5], v[4:5], v[236:237] op_sel_hi:[1,0]
	v_pk_mul_f32 v[2:3], v[2:3], v[236:237] op_sel_hi:[1,0]
